# P2 queue: next attention item claimed at the start of the current one, index parked in v236 lane 63, fetch uses it instead of a synchronous atomic
# baseline (speedup 1.0000x reference)
; DI void attn_item(const Params& p, unsigned char* lds, int b, int hd, int qb, float lam) {
;     ...
;     const bf16_t* aq = (const bf16_t*)((unsigned char*)p.out + DO_AQ);
;     const bf16_t* ak = (const bf16_t*)(p.ws + OFF_AK);
;     const bf16_t* avT = (const bf16_t*)(p.ws + OFF_AVT);
;     const bf16_t* akm = (const bf16_t*)(p.ws + OFF_AKM);
;     const bf16_t* avTm = (const bf16_t*)(p.ws + OFF_AVTM);
;     bf16_t* az = (bf16_t*)(p.ws + OFF_AZ);
; DI void phase2(const Params& p, unsigned char* lds) {
;     ...
;     float lam;
;     {
;         const int lane = tid & 63;
;         const float a_ = wave_sum(p.lq1[lane] * p.lk1[lane]);
;         const float b_ = wave_sum(p.lq2[lane] * p.lk2[lane]);
;         lam = __uint_as_float((unsigned)__builtin_amdgcn_readfirstlane((int)__float_as_uint(expf(a_) - expf(b_) + 0.2f)));
;     }
;     volatile unsigned* sItem = (volatile unsigned*)(lds + LDS_ITEM);
;     constexpr unsigned NSL = 8 / GLA_DL, N_GLA = 2 * NSL, N_ATT = 128;
;     if (tid == 0) sItem[1] = 0u;
.LBB0_1798:
	s_or_b64 exec, exec, s[4:5]
	s_add_u32 s58, s70, 0xff20c00
	s_addc_u32 s59, s71, 0
	s_add_u32 s60, s70, 0x3840000
	s_addc_u32 s61, s71, 0
	s_add_u32 s62, s70, 0xf930500
	s_addc_u32 s63, s71, 0
	s_add_u32 s64, s70, 0xf910500
	s_addc_u32 s65, s71, 0
	s_add_u32 s44, s70, 0x1840000
	s_addc_u32 s45, s71, 0
	s_add_u32 s46, s70, 0x5840000
	s_addc_u32 s47, s71, 0
	s_add_u32 s66, s68, 0x2000000
	s_addc_u32 s67, s69, 0
	s_add_u32 s76, s68, 0x3000000
	s_addc_u32 s77, s69, 0
	s_add_u32 s78, s70, 0x7840000
	s_addc_u32 s79, s71, 0
	s_add_u32 s3, s70, 0xf994700
	s_addc_u32 s33, s71, 0
	s_add_u32 s48, s70, 0x9840000
	s_addc_u32 s49, s71, 0
	s_add_u32 s2, s70, 0xfa14f00
	s_addc_u32 s1, s71, 0
	s_add_u32 s80, s70, 0xf974700
	s_addc_u32 s81, s71, 0
	s_add_u32 s82, s70, 0xf950500
	s_addc_u32 s83, s71, 0
	s_add_u32 s84, s70, 0xf984700
	v_mov_b32_e32 v0, 0x3e4ccccd
	s_addc_u32 s85, s71, 0
	s_mov_b64 s[56:57], src_shared_base
	v_add_f32_e32 v133, s0, v0
	s_add_u32 s86, s70, 0xfa14700
	s_addc_u32 s87, s71, 0
	v_mov_b32_e32 v134, v133
	v_mov_b32_e32 v135, v133
	s_add_i32 s42, 0, 0x25004
	v_mov_b32_e32 v187, 1
	v_writelane_b32 v236, -1, 63
	v_mov_b32_e32 v99, 0
	s_mov_b32 s43, 0x10000
	s_movk_i32 s56, 0x2000
	s_mov_b32 s74, 0x80000
	s_movk_i32 s75, 0x110
	s_movk_i32 s52, 0x90
	v_mov_b32_e32 v188, 0xff800000
	s_mov_b64 s[88:89], 0x80
	s_mov_b64 s[90:91], 0x20000
	v_mov_b32_e32 v189, 0x3727c5ac
	v_mov_b32_e32 v190, 0x260
	s_add_i32 s51, 0, 0x6800
	s_mov_b32 s53, 0x8000
	s_mov_b64 s[92:93], 0x10000
	s_mov_b64 s[94:95], 0x800
	v_bfrev_b32_e32 v0, 1
	s_branch .LBB0_1801

; DI void phase2(const Params& p, unsigned char* lds) {
;     ...
;         if (tid == 0) {
;             unsigned* heads = (unsigned*)(p.ws + OFF_XBAR + 15360);
;             const unsigned x0 = (unsigned)__builtin_amdgcn_s_getreg((3 << 11) | 20) & 7u;
;             unsigned k = sItem[1], it = 0xffffffffu;
;             while (k < 8u) {
;                 const unsigned x = (x0 + k) & 7u;
;                 const unsigned got = atomicAdd(heads + x, 1u);
;                 if (got < N_GLA + N_ATT) { it = got | (x << 16); break; }
;                 ++k;
;             }
;             sItem[1] = k; sItem[0] = it;
.LBB0_1804:
	s_waitcnt lgkmcnt(0)
	v_mov_b32_e32 v1, v3
	v_cmp_gt_u32_e32 vcc, 8, v1
	s_or_b64 s[10:11], s[10:11], exec
	s_or_b64 s[12:13], s[12:13], exec
	s_and_saveexec_b64 s[14:15], vcc
	s_cbranch_execz .LBB0_1803
	v_add_u32_e32 v2, s0, v1
	v_and_b32_e32 v2, 7, v2
	v_lshlrev_b32_e32 v3, 2, v2
	v_readlane_b32 s16, v236, 63
	s_cmp_eq_u32 s16, -1
	s_cbranch_scc1 .Lq_nopark
	v_mov_b32_e32 v4, s16
	v_writelane_b32 v236, -1, 63
	s_branch .Lq_parked
.Lq_nopark:
	global_atomic_add v4, v3, v187, s[58:59] sc0
.Lq_parked:
	s_movk_i32 s16, 0x88
	s_andn2_b64 s[12:13], s[12:13], exec
	v_add_u32_e32 v3, 1, v1
	s_andn2_b64 s[10:11], s[10:11], exec
	s_waitcnt vmcnt(0)
	v_cmp_gt_u32_e32 vcc, s16, v4
	s_and_b64 s[16:17], vcc, exec
	s_or_b64 s[12:13], s[12:13], s[16:17]
	s_branch .LBB0_1803

; DI void attn_item(const Params& p, unsigned char* lds, int b, int hd, int qb, float lam) {
;     ...
;     const int qs = qb * 128 + rt * 32 + l31;
;     const size_t grow = (size_t)b * 4096 + qs;
;     bf16x8 qf[4];
; #pragma unroll
;     for (int ks = 0; ks < 4; ++ks) qf[ks] = *(const bf16x8*)(aq + grow * 1024 + hd * 128 + sub * 64 + ks * 16 + 8 * h);
;     f32x16 O[4];
; #pragma unroll
;     for (int d = 0; d < 4; ++d)
; #pragma unroll
;         for (int i = 0; i < 16; ++i) O[d][i] = 0.f;
;     float m = 0.f, l = 0.f;
;     const int T = 2 * qb + 3;
;     u32x4 k0r[2], v0r[2];
;     const int krow_ = tid >> 4, kc_ = tid & 15, vdv_ = tid >> 3, vc_ = tid & 7;
;     const bf16_t* kp = ak + ((size_t)b * 4096 + krow_) * 1024 + hd * 128 + kc_ * 8;
;     const bf16_t* vp_ = avT + ((size_t)(b * 8 + hd) * 128 + vdv_) * 4096 + vc_ * 8;
;     ...
;     {
;         const bf16_t* km_ = akm + (size_t)krow_ * 1024 + hd * 128 + kc_ * 8;
;         k0r[0] = *(const u32x4*)km_; k0r[1] = *(const u32x4*)(km_ + 32 * 1024);
;         const bf16_t* vm_ = avTm + (size_t)(hd * 128 + vdv_) * 64 + vc_ * 8;
;         v0r[0] = *(const u32x4*)vm_; v0r[1] = *(const u32x4*)(vm_ + 64 * 64);
;     }
;     u32x4 k1r[2], v1r[2];
;     A_LOAD_REAL(k1r, v1r);
; #pragma unroll
;     for (int ks = 0; ks < 4; ++ks) asm volatile("" : "+v"(qf[ks]));
;     A_STORE(k0r, v0r, 0);
;     __syncthreads();
; DI void phase2(const Params& p, unsigned char* lds) {
;     ...
;         const unsigned item = (unsigned)__builtin_amdgcn_readfirstlane((int)sItem[0]);
;         __syncthreads();
;         if (item == 0xffffffffu) break;
;         const unsigned x = item >> 16, idx = item & 0xffffu;
;         if (idx < N_GLA) { const unsigned gi = x * N_GLA + idx; gla_item<GLA_DL>(p, lds, gi / (4 * NSL), (gi / NSL) & 3, gi % NSL); }
;         else { const unsigned a = idx - N_GLA, pair = 4 * x + ((a >> 2) & 3); attn_item(p, lds, pair & 3, pair >> 2, 31 - (int)(((a >> 4) << 2) + (a & 3)), lam); }
.LBB0_1809:
	s_or_b64 exec, exec, s[4:5]
	s_add_i32 s0, 0, 0x25000
	s_cmp_lg_u32 s0, -1
	s_cselect_b32 s0, s0, 0
	s_cselect_b32 s4, s57, 0
	s_waitcnt vmcnt(0)
	v_mov_b32_e32 v2, s0
	v_mov_b32_e32 v3, s4
	s_waitcnt lgkmcnt(0)
	s_barrier
	ds_read_b32 v1, v2
	s_waitcnt vmcnt(0) lgkmcnt(0)
	s_barrier
	v_readfirstlane_b32 s8, v1
	s_cmp_eq_u32 s8, -1
	s_cbranch_scc1 .LBB0_1823
	s_lshr_b32 s9, s8, 16
	s_and_b32 s0, s8, 0xffff
	s_cmp_gt_u32 s0, 7
	s_mov_b64 s[4:5], -1
	s_cbranch_scc0 .LBB0_1831
	s_and_saveexec_b64 s[4:5], s[40:41]
	v_lshlrev_b32_e64 v238, 2, s9
	s_nop 0
	global_atomic_add v238, v238, v187, s[58:59] sc0
	s_mov_b64 exec, s[4:5]
	s_add_i32 s4, s0, -8
	s_lshr_b32 s0, s4, 2
	s_and_b32 s0, s0, 0x3ffffffc
	s_and_b32 s5, s8, 3
	s_or_b32 s0, s0, s5
	v_mov_b32_e32 v132, v186
	s_sub_i32 s0, 31, s0
	s_lshl_b32 s6, s0, 7
	v_lshrrev_b32_e32 v1, 1, v132
	v_and_b32_e32 v146, 31, v132
	v_and_b32_e32 v148, 0x60, v1
	s_bfe_u32 s11, s4, 0x20002
	v_or3_b32 v138, v148, s6, v146
	s_lshl_b32 s54, s11, 12
	v_ashrrev_i32_e32 v139, 31, v138
	v_lshl_add_u64 v[2:3], v[138:139], 0, s[54:55]
	v_ashrrev_i32_e32 v147, 8, v132
	v_lshlrev_b64 v[136:137], 11, v[2:3]
	v_lshl_add_u64 v[2:3], s[68:69], 0, v[136:137]
	s_lshl_b32 s6, s9, 8
	s_mov_b32 s7, s55
	v_lshlrev_b32_e32 v4, 6, v147
	v_lshl_add_u64 v[2:3], v[2:3], 0, s[6:7]
	v_ashrrev_i32_e32 v5, 31, v4
	v_lshl_add_u64 v[2:3], v[4:5], 1, v[2:3]
	v_ashrrev_i32_e32 v4, 4, v132
	v_ashrrev_i32_e32 v5, 31, v4
	v_lshlrev_b64 v[12:13], 11, v[4:5]
	v_bfe_u32 v149, v132, 5, 1
	v_lshlrev_b32_e32 v1, 4, v132
	v_lshl_add_u64 v[12:13], s[64:65], 0, v[12:13]
	v_lshlrev_b32_e32 v98, 4, v149
	v_and_b32_e32 v140, 0xf0, v1
	v_mov_b32_e32 v141, v99
	v_lshl_add_u64 v[12:13], v[12:13], 0, s[6:7]
	v_lshl_add_u64 v[2:3], v[2:3], 0, v[98:99]
	v_lshl_add_u64 v[12:13], v[12:13], 0, v[140:141]
	global_load_dwordx4 v[100:103], v[2:3], off
	global_load_dwordx4 v[104:107], v[2:3], off offset:32
	global_load_dwordx4 v[108:111], v[2:3], off offset:64
	global_load_dwordx4 v[112:115], v[2:3], off offset:96
	global_load_dwordx4 v[116:119], v[12:13], off
	v_add_co_u32_e32 v2, vcc, s43, v12
	s_lshl_b32 s10, s9, 7
	v_ashrrev_i32_e32 v6, 3, v132
	v_addc_co_u32_e32 v3, vcc, 0, v13, vcc
	global_load_dwordx4 v[120:123], v[2:3], off
	v_add_u32_e32 v2, s10, v6
	v_ashrrev_i32_e32 v3, 31, v2
	v_lshlrev_b64 v[2:3], 7, v[2:3]
	v_and_b32_e32 v10, 0x70, v1
	v_mov_b32_e32 v11, v99
	v_lshl_add_u64 v[2:3], s[62:63], 0, v[2:3]
	v_lshl_add_u64 v[2:3], v[2:3], 0, v[10:11]
	global_load_dwordx4 v[124:127], v[2:3], off
	v_lshl_add_u64 v[8:9], v[4:5], 0, s[54:55]
	v_lshlrev_b64 v[8:9], 11, v[8:9]
	v_add_co_u32_e32 v2, vcc, s56, v2
	v_lshl_add_u64 v[8:9], s[44:45], 0, v[8:9]
	s_lshl_b32 s11, s11, 10
	v_addc_co_u32_e32 v3, vcc, 0, v3, vcc
	v_lshl_add_u64 v[8:9], v[8:9], 0, s[6:7]
	s_add_i32 s54, s11, s10
	v_ashrrev_i32_e32 v7, 31, v6
	global_load_dwordx4 v[128:131], v[2:3], off
	v_lshl_add_u64 v[82:83], v[8:9], 0, v[140:141]
	v_lshl_add_u64 v[8:9], v[6:7], 0, s[54:55]
	v_lshlrev_b64 v[8:9], 13, v[8:9]
	v_lshl_add_u64 v[8:9], s[60:61], 0, v[8:9]
	v_add_co_u32_e32 v2, vcc, s43, v82
	v_lshl_add_u64 v[84:85], v[8:9], 0, v[10:11]
	s_nop 0
	v_addc_co_u32_e32 v3, vcc, 0, v83, vcc
	v_add_co_u32_e32 v8, vcc, s74, v84
	global_load_dwordx4 v[74:77], v[82:83], off
	global_load_dwordx4 v[70:73], v[84:85], off
	v_addc_co_u32_e32 v9, vcc, 0, v85, vcc
	global_load_dwordx4 v[78:81], v[2:3], off
	global_load_dwordx4 v[66:69], v[8:9], off
	v_lshlrev_b32_e32 v2, 3, v132
	v_mul_lo_u32 v139, v4, s75
	v_add_u32_e32 v4, 0x200, v132
	v_and_b32_e32 v150, 0x60, v1
	v_and_b32_e32 v151, 8, v2
	v_lshrrev_b32_e32 v5, 4, v4
	v_add3_u32 v1, 0, v150, v151
	v_mul_lo_u32 v152, v6, s52
	v_add_u32_e32 v3, 0, v140
	v_mul_lo_u32 v141, v5, s75
	v_add_u32_e32 v97, v1, v152
	v_add_u32_e32 v87, v3, v139
	v_add_u32_e32 v96, v3, v141
	v_add_u32_e32 v2, 0x4000, v97
	s_waitcnt vmcnt(11)
	s_waitcnt vmcnt(10)
	s_waitcnt vmcnt(9)
	s_waitcnt vmcnt(8)
	s_waitcnt vmcnt(7)
	ds_write_b128 v87, v[116:119]
	v_mad_u32_u24 v42, v146, s75, 0
	v_lshl_or_b32 v154, v147, 7, v98
	s_waitcnt vmcnt(6)
	ds_write_b128 v96, v[120:123]
	s_waitcnt vmcnt(5)
	ds_write2_b64 v2, v[124:125], v[126:127] offset0:128 offset1:130
	v_lshrrev_b32_e32 v2, 3, v4
	v_mul_lo_u32 v153, v2, s52
	v_add_u32_e32 v155, v1, v153
	v_add_u32_e32 v1, 0x4000, v155
	s_waitcnt vmcnt(4)
	ds_write2_b64 v1, v[128:129], v[130:131] offset0:128 offset1:130
	v_add_u32_e32 v1, v42, v154
	s_waitcnt lgkmcnt(0)
	s_barrier
; DI void attn_s(const unsigned char* sK, int tt, int qb, int qs, int sub, int l31, int h,
;                const bf16x8 (&qf)[4], f32x16 (&O)[4], float& m, float& l, bf16x8 (&pb)[4]) {
;     ...
;     if (tt == 0) {
; #pragma unroll
;         for (int i = 0; i < 16; ++i) { st[0][i] = -INFINITY; if (i < 8) st[1][i] = -INFINITY; }
;     } else if (tt >= 2 * qb + 1) {
;         const int kbase = (tt - 1) * 64 + 4 * h;
; #pragma unroll
;         for (int k2 = 0; k2 < 2; ++k2)
; #pragma unroll
;             for (int i = 0; i < 16; ++i) {
;                 const int key = kbase + k2 * 32 + (i & 3) + 8 * (i >> 2);
;                 if (key > qs) st[k2][i] = -INFINITY;
;             }
;     }
;     float mx;
;     {
;         float t[11];
; #pragma unroll
;         for (int i = 0; i < 5; ++i) t[i] = max3f(st[0][3 * i], st[0][3 * i + 1], st[0][3 * i + 2]);
; #pragma unroll
;         for (int i = 0; i < 5; ++i) t[5 + i] = max3f(st[1][3 * i], st[1][3 * i + 1], st[1][3 * i + 2]);
;         t[10] = fmaxf(st[0][15], st[1][15]);
;         const float u0 = max3f(t[0], t[1], t[2]), u1 = max3f(t[3], t[4], t[5]), u2 = max3f(t[6], t[7], t[8]);
;         mx = max3f(max3f(u0, u1, u2), t[9], t[10]);
;     }
;     mx = xor32_max(mx);
;     if (tt == 0 || __builtin_amdgcn_ballot_w64(mx > 8.0f) != 0ull) {
;         const float delta = tt == 0 ? mx : fmaxf(mx, 0.f);
;         const float alpha = __builtin_amdgcn_exp2f(-delta);
;         m += delta;
;         l *= alpha;
; #pragma unroll
;         for (int d = 0; d < 4; ++d) O[d] = O[d] * alpha;
; #pragma unroll
;         for (int k2 = 0; k2 < 2; ++k2) st[k2] = st[k2] - delta;
;     }
; #pragma unroll
;     for (int k2 = 0; k2 < 2; ++k2)
; #pragma unroll
;         for (int i = 0; i < 16; ++i) st[k2][i] = __builtin_amdgcn_exp2f(st[k2][i]);
;     {
;         const f32x16 sv = st[0] + st[1];
;         const float ps = (((sv[0] + sv[1]) + (sv[2] + sv[3])) + ((sv[4] + sv[5]) + (sv[6] + sv[7]))) + (((sv[8] + sv[9]) + (sv[10] + sv[11])) + ((sv[12] + sv[13]) + (sv[14] + sv[15])));
;         l += ps;
;     }
; #pragma unroll
;     for (int k4 = 0; k4 < 4; ++k4) {
;         const int k2 = k4 >> 1, o8 = 8 * (k4 & 1);
;         u32x4 pk;
;         pk.x = pk2(st[k2][o8 + 0], st[k2][o8 + 1]); pk.y = pk2(st[k2][o8 + 2], st[k2][o8 + 3]);
;         pk.z = pk2(st[k2][o8 + 4], st[k2][o8 + 5]); pk.w = pk2(st[k2][o8 + 6], st[k2][o8 + 7]);
	ds_read_b128 v[26:29], v1 offset:8704
	ds_read_b128 v[30:33], v1 offset:8736
	ds_read_b128 v[34:37], v1 offset:8768
	ds_read_b128 v[38:41], v1 offset:8800
	v_mov_b32_e32 v10, v0
	v_mov_b32_e32 v11, v0
	v_mov_b32_e32 v12, v0
	v_mov_b32_e32 v13, v0
	v_mov_b32_e32 v14, v0
	v_mov_b32_e32 v15, v0
	v_mov_b32_e32 v1, v0
	v_mov_b32_e32 v2, v0
	v_mov_b32_e32 v3, v0
	v_mov_b32_e32 v4, v0
	v_mov_b32_e32 v5, v0
	v_mov_b32_e32 v6, v0
	v_mov_b32_e32 v7, v0
	v_mov_b32_e32 v8, v0
	v_mov_b32_e32 v9, v0
	v_mov_b64_e32 v[24:25], v[14:15]
	v_mov_b64_e32 v[22:23], v[12:13]
	v_mov_b64_e32 v[20:21], v[10:11]
	v_mov_b64_e32 v[18:19], v[8:9]
	v_mov_b64_e32 v[16:17], v[6:7]
	v_mov_b64_e32 v[14:15], v[4:5]
	v_mov_b64_e32 v[12:13], v[2:3]
	v_mov_b64_e32 v[10:11], v[0:1]
	s_waitcnt lgkmcnt(3)
	s_nop 0
	v_mfma_f32_32x32x16_bf16 v[10:25], v[26:29], v[100:103], v[10:25]
	s_waitcnt lgkmcnt(2)
	v_mfma_f32_32x32x16_bf16 v[10:25], v[30:33], v[104:107], v[10:25]
	s_waitcnt lgkmcnt(1)
	v_mfma_f32_32x32x16_bf16 v[10:25], v[34:37], v[108:111], v[10:25]
	v_max3_f32 v1, v188, v188, v188
	s_nop 0
	v_max3_f32 v2, v1, v1, v1
	s_waitcnt lgkmcnt(0)
	v_mfma_f32_32x32x16_bf16 v[10:25], v[38:41], v[112:115], v[10:25]
	v_max3_f32 v3, v188, v188, v18
	v_max3_f32 v4, v19, v20, v21
	v_max3_f32 v5, v22, v23, v24
	s_nop 0
	v_max3_f32 v1, v1, v3, v4
	s_nop 10
	v_max_f32_e32 v6, v25, v25
	v_max3_f32 v1, v2, v2, v1
	v_max_f32_e32 v6, 0xff800000, v6
	v_max3_f32 v1, v1, v5, v6
	s_nop 0
	v_mov_b32_e32 v2, v1
	s_nop 1
	v_permlane32_swap_b32_e32 v1, v2
	v_max_f32_e32 v2, v2, v2
	v_max_f32_e32 v1, v1, v1
	v_max_f32_e32 v86, v1, v2
	v_sub_f32_e32 v1, 0xff800000, v86
	v_sub_f32_e32 v19, v19, v86
	v_sub_f32_e32 v26, v18, v86
	v_sub_f32_e32 v21, v21, v86
	v_sub_f32_e32 v20, v20, v86
	v_exp_f32_e32 v18, v1
	v_exp_f32_e32 v26, v26
	v_exp_f32_e32 v27, v19
	v_sub_f32_e32 v23, v23, v86
	v_sub_f32_e32 v22, v22, v86
	v_exp_f32_e32 v28, v20
	v_exp_f32_e32 v29, v21
	v_sub_f32_e32 v25, v25, v86
	v_sub_f32_e32 v24, v24, v86
	v_exp_f32_e32 v30, v22
	v_exp_f32_e32 v31, v23
	v_exp_f32_e32 v32, v24
	v_exp_f32_e32 v33, v25
	v_pk_add_f32 v[34:35], v[18:19], v[26:27] op_sel_hi:[0,1]
	v_add_f32_e32 v36, v18, v18
	v_pk_add_f32 v[24:25], v[18:19], v[28:29] op_sel_hi:[0,1]
	v_mov_b32_e32 v37, v34
	v_mov_b32_e32 v34, v36
	v_pk_add_f32 v[22:23], v[18:19], v[30:31] op_sel_hi:[0,1]
	v_pk_add_f32 v[34:35], v[36:37], v[34:35]
	v_mov_b32_e32 v37, v24
	v_mov_b32_e32 v24, v36
	v_pk_add_f32 v[20:21], v[18:19], v[32:33] op_sel_hi:[0,1]
	v_pk_add_f32 v[24:25], v[36:37], v[24:25]
	v_mov_b32_e32 v37, v22
	v_mov_b32_e32 v22, v36
	v_pk_add_f32 v[22:23], v[36:37], v[22:23]
	v_mov_b32_e32 v37, v20
	v_mov_b32_e32 v20, v36
	v_pk_add_f32 v[20:21], v[36:37], v[20:21]
	v_cvt_pk_bf16_f32 v88, v18, v18
	v_lshlrev_b32_e32 v18, 7, v146
	v_pk_add_f32 v[24:25], v[34:35], v[24:25]
	v_pk_add_f32 v[20:21], v[22:23], v[20:21]
	v_sub_u32_e32 v18, v42, v18
	v_pk_add_f32 v[20:21], v[24:25], v[20:21]
	v_add_u32_e32 v185, v18, v98
	v_add_f32_e32 v1, v20, v21
	ds_read_b128 v[18:21], v185 offset:17408
	ds_read_b128 v[22:25], v185 offset:22016
	ds_read_b128 v[92:95], v185 offset:26624
	ds_read_b128 v[142:145], v185 offset:31232
	v_exp_f32_e64 v184, -v86
	v_mov_b32_e32 v89, v88
	v_mov_b32_e32 v90, v88
	v_mov_b32_e32 v91, v88
	v_mul_f32_e32 v2, 0, v184
	v_mov_b32_e32 v3, v2
	v_mov_b32_e32 v4, v2
	v_mov_b32_e32 v5, v2
	v_mov_b32_e32 v6, v2
	v_mov_b32_e32 v7, v2
	v_mov_b32_e32 v8, v2
	v_mov_b32_e32 v9, v2
	v_mov_b32_e32 v10, v2
	v_mov_b32_e32 v11, v2
	v_mov_b32_e32 v12, v2
	v_mov_b32_e32 v13, v2
	v_mov_b32_e32 v14, v2
	v_mov_b32_e32 v15, v2
	v_mov_b32_e32 v16, v2
	v_mov_b32_e32 v17, v2
	v_cvt_pk_bf16_f32 v156, v26, v27
	v_cvt_pk_bf16_f32 v157, v28, v29
	v_cvt_pk_bf16_f32 v158, v30, v31
	v_cvt_pk_bf16_f32 v159, v32, v33
	ds_read_b128 v[160:163], v185 offset:17440
	ds_read_b128 v[164:167], v185 offset:22048
	ds_read_b128 v[168:171], v185 offset:26656
	ds_read_b128 v[172:175], v185 offset:31264
	s_waitcnt lgkmcnt(7)
	v_mfma_f32_32x32x16_bf16 v[50:65], v[18:21], v[88:91], v[2:17]
	s_waitcnt lgkmcnt(6)
	v_mfma_f32_32x32x16_bf16 v[34:49], v[22:25], v[88:91], v[2:17]
	s_waitcnt lgkmcnt(5)
	v_mfma_f32_32x32x16_bf16 v[18:33], v[92:95], v[88:91], v[2:17]
	s_waitcnt lgkmcnt(4)
	v_mfma_f32_32x32x16_bf16 v[2:17], v[142:145], v[88:91], v[2:17]
	ds_read_b128 v[92:95], v185 offset:17472
	ds_read_b128 v[142:145], v185 offset:22080
	ds_read_b128 v[176:179], v185 offset:26688
	ds_read_b128 v[180:183], v185 offset:31296
	s_waitcnt lgkmcnt(7)
	v_mfma_f32_32x32x16_bf16 v[50:65], v[160:163], v[88:91], v[50:65]
	s_waitcnt lgkmcnt(6)
	v_mfma_f32_32x32x16_bf16 v[34:49], v[164:167], v[88:91], v[34:49]
	s_waitcnt lgkmcnt(5)
	v_mfma_f32_32x32x16_bf16 v[18:33], v[168:171], v[88:91], v[18:33]
	s_waitcnt lgkmcnt(4)
	v_mfma_f32_32x32x16_bf16 v[2:17], v[172:175], v[88:91], v[2:17]
	ds_read_b128 v[160:163], v185 offset:17504
	ds_read_b128 v[164:167], v185 offset:22112
	ds_read_b128 v[168:171], v185 offset:26720
	ds_read_b128 v[172:175], v185 offset:31328
	s_waitcnt lgkmcnt(7)
	v_mfma_f32_32x32x16_bf16 v[50:65], v[92:95], v[88:91], v[50:65]
	s_waitcnt lgkmcnt(6)
	v_mfma_f32_32x32x16_bf16 v[34:49], v[142:145], v[88:91], v[34:49]
	s_waitcnt lgkmcnt(5)
	v_mfma_f32_32x32x16_bf16 v[18:33], v[176:179], v[88:91], v[18:33]
	s_waitcnt lgkmcnt(4)
	v_mfma_f32_32x32x16_bf16 v[2:17], v[180:183], v[88:91], v[2:17]
	s_waitcnt lgkmcnt(3)
	v_mfma_f32_32x32x16_bf16 v[50:65], v[160:163], v[156:159], v[50:65]
	s_waitcnt vmcnt(3)
	ds_write_b128 v87, v[74:77] offset:35840
	s_waitcnt vmcnt(1)
	ds_write_b128 v96, v[78:81] offset:35840
	v_add_u32_e32 v74, 0xd000, v97
	ds_write2_b64 v74, v[70:71], v[72:73] offset1:2
	v_add_u32_e32 v70, 0xd000, v155
	v_fmac_f32_e32 v1, 0, v184
	s_cmpk_gt_u32 s4, 0x7f
	s_waitcnt vmcnt(0)
	ds_write2_b64 v70, v[66:67], v[68:69] offset1:2
	v_readfirstlane_b32 s99, v238
	s_nop 3
	v_writelane_b32 v236, s99, 63
	s_waitcnt lgkmcnt(6)
	v_mfma_f32_32x32x16_bf16 v[34:49], v[164:167], v[156:159], v[34:49]
	s_waitcnt lgkmcnt(0)
	s_barrier
; DI void attn_s(const unsigned char* sK, int tt, int qb, int qs, int sub, int l31, int h,
;                const bf16x8 (&qf)[4], f32x16 (&O)[4], float& m, float& l, bf16x8 (&pb)[4]) {
;     ...
;     for (int k2 = 0; k2 < 2; ++k2)
; #pragma unroll
;         for (int i = 0; i < 16; ++i) st[k2][i] = -m;
; DI void attn_item(const Params& p, unsigned char* lds, int b, int hd, int qb, float lam) {
;     ...
;     for (int tt = 1; tt < T; ++tt) {
;         if (tt + 1 < T) A_LOAD_REAL(k0r, v0r);
;         attn_s(lds + bc * A_STAGE, tt, qb, qs, sub, l31, h, qf, O, m, l, pb);
	v_mfma_f32_32x32x16_bf16 v[18:33], v[168:171], v[156:159], v[18:33]
	v_mfma_f32_32x32x16_bf16 v[2:17], v[172:175], v[156:159], v[2:17]
	s_cbranch_scc1 .LBB0_1824
	s_lshr_b32 s4, s4, 1
	s_lshl_b32 s5, s5, 1
	s_and_b32 s4, s4, 0x7ffffff8
	s_lshl_b32 s0, s0, 1
	s_or_b32 s4, s5, s4
	v_mul_u32_u24_e32 v155, 0x110, v146
	v_mul_u32_u24_e32 v156, 0x90, v146
	s_mov_b32 s13, 1
	s_add_i32 s6, s0, 3
	v_lshl_add_u64 v[142:143], v[84:85], 0, s[88:89]
	v_lshl_add_u64 v[142:143], v[142:143], 0, s[88:89]
	v_add_f32_e32 v157, 0, v86
	v_lshl_add_u64 v[144:145], v[82:83], 0, s[90:91]
	v_lshl_add_u64 v[144:145], v[144:145], 0, s[90:91]
	s_mov_b32 s7, 2
	v_lshl_or_b32 v158, v149, 2, 59
	s_sub_i32 s11, 0, s4
	s_movk_i32 s12, 0xffc0
	v_xor_b32_e32 v240, 0x80000000, v157
	v_mov_b32_e32 v241, v240
	v_mov_b32_e32 v242, v240
	v_mov_b32_e32 v243, v240
	v_mov_b32_e32 v244, v240
	v_mov_b32_e32 v245, v240
	v_mov_b32_e32 v246, v240
	v_mov_b32_e32 v247, v240
	v_mov_b32_e32 v248, v240
	v_mov_b32_e32 v249, v240
	v_mov_b32_e32 v250, v240
	v_mov_b32_e32 v251, v240
	v_mov_b32_e32 v252, v240
	v_mov_b32_e32 v253, v240
	v_mov_b32_e32 v254, v240
	v_mov_b32_e32 v255, v240
	v_readfirstlane_b32 s99, v147
	s_cmp_eq_u32 s99, 1
	s_cbranch_scc0 .Lpipe_nooffs
	s_barrier
